# decode-attention item prologues: page-table entry requested before the Q staging loads; Q staging requests both rows before waiting (one round trip instead of up to three per item)
# baseline (speedup 1.0000x reference)
.LBB0_2264:
	s_load_dwordx2 s[4:5], s[4:5], 0x10
	s_nop 0
	s_load_dwordx2 s[8:9], s[8:9], 0x18
	s_nop 0
	s_load_dwordx2 s[18:19], s[16:17], 0x20
	v_and_b32_e32 v155, 15, v34
	s_andn2_b64 vcc, exec, s[20:21]
	s_ashr_i32 s16, s14, 1
	s_lshl_b32 s98, s14, 5
	s_lshl_b32 s99, s16, 6
	s_and_b32 s98, s98, 32
	s_or_b32 s99, s99, s98
	s_lshl_b32 s98, s1, 2
	s_add_i32 s98, s99, s98
	s_ashr_i32 s99, s98, 31
	s_lshl_b64 s[98:99], s[98:99], 2
	s_waitcnt lgkmcnt(0)
	s_add_u32 s98, s18, s98
	s_addc_u32 s99, s19, s99
	global_load_dwordx4 v[236:239], v1, s[98:99]
	s_cbranch_vccnz .LBB0_2268
	s_lshl_b32 s10, s1, 10
	s_lshl_b32 s20, s1, 5
	s_add_i32 s10, s10, 0
	s_ashr_i32 s21, s20, 31
	s_add_i32 s2, s1, -8
	s_add_i32 s10, s10, 0x21000
	s_mul_i32 s15, s16, 0x2800
	s_lshl_b64 s[20:21], s[20:21], 1
	v_add_u32_e32 v3, s10, v2
	s_mul_hi_i32 s10, s16, 0x2800
	s_add_u32 s15, s20, s15
	v_mul_u32_u24_e32 v6, 0x140, v155
	s_addc_u32 s10, s21, s10
	v_mov_b64_e32 v[150:151], v[0:1]
	v_and_or_b32 v4, v34, 48, s15
	v_mov_b32_e32 v5, s10
	v_lshlrev_b32_e32 v0, 1, v6
	v_lshl_add_u64 v[4:5], v[4:5], 0, v[0:1]
	v_lshl_add_u64 v[4:5], s[58:59], 0, v[4:5]
.LBB0_2266:
	global_load_dwordx4 v[6:9], v[4:5], off
	s_add_i32 s2, s2, 8
	s_mov_b64 s[20:21], 0x200
	v_lshl_add_u64 v[4:5], v[4:5], 0, s[20:21]
	s_cmp_gt_i32 s2, 1
	s_cbranch_scc1 .Lmy_q1_a2a
	global_load_dwordx4 v[248:251], v[4:5], off
	s_add_i32 s2, s2, 8
	v_lshl_add_u64 v[4:5], v[4:5], 0, s[20:21]
	s_waitcnt vmcnt(0)
	ds_write_b128 v3, v[6:9]
	v_add_u32_e32 v3, 0x2000, v3
	ds_write_b128 v3, v[248:251]
	v_add_u32_e32 v3, 0x2000, v3
	s_cmp_gt_i32 s2, 1
	s_cbranch_scc0 .LBB0_2266
	s_branch .Lmy_q2_a2a
.Lmy_q1_a2a:
	s_waitcnt vmcnt(0)
	ds_write_b128 v3, v[6:9]
	v_add_u32_e32 v3, 0x2000, v3
.Lmy_q2_a2a:
	v_mov_b32_e32 v39, v2
.LBB0_2268:
	s_lshl_b32 s17, s14, 5
	s_lshl_b32 s15, s16, 6
	s_and_b32 s17, s17, 32
	s_or_b32 s15, s15, s17
	s_lshl_b32 s17, s1, 2
	s_add_i32 s20, s15, s17
	s_lshl_b32 s2, s1, 14
	s_ashr_i32 s21, s20, 31
	s_add_i32 s10, s2, 0
	s_ashr_i32 s2, s1, 31
	s_lshl_b64 s[20:21], s[20:21], 2
	s_waitcnt lgkmcnt(0)
	s_add_u32 s18, s18, s20
	s_addc_u32 s19, s19, s21
	v_mov_b32_e32 v3, v1
	s_barrier
	v_lshlrev_b32_e32 v0, 3, v36
	v_lshlrev_b32_e32 v38, 2, v36
	v_and_b32_e32 v36, 0x1f0, v0
	v_add_u32_e32 v41, s10, v36
	v_xad_u32 v42, v36, 32, s10
	v_xad_u32 v43, v36, 64, s10
	v_lshrrev_b32_e32 v37, 2, v155
	v_and_b32_e32 v40, 8, v0
	v_lshl_add_u32 v46, v155, 9, s10
	v_xor_b32_e32 v163, 64, v38
	v_xor_b32_e32 v164, 0x80, v38
	v_add_u32_e32 v182, v41, v40
	v_add_u32_e32 v183, v42, v40
	v_add_u32_e32 v184, v43, v40
	s_mov_b32 s15, 4
	s_mov_b32 s17, 0
	v_mov_b32_e32 v165, 0
	v_mov_b32_e32 v154, 0xf149f2ca
	s_movk_i32 s38, 0x2000
	s_waitcnt vmcnt(0)
	v_readfirstlane_b32 s24, v237
	v_readfirstlane_b32 s20, v236
	s_ashr_i32 s21, s20, 31
	s_ashr_i32 s25, s24, 31
	s_lshl_b64 s[22:23], s[24:25], 17
	s_lshl_b64 s[18:19], s[20:21], 17
	s_add_u32 s18, s4, s18
	s_addc_u32 s19, s5, s19
	v_lshl_add_u64 v[10:11], s[18:19], 0, v[2:3]
	v_add_co_u32_e32 v10, vcc, s96, v10
	v_readfirstlane_b32 s34, v239
	s_nop 0
	v_addc_co_u32_e32 v11, vcc, 0, v11, vcc
	v_readfirstlane_b32 s28, v238
	global_load_dwordx4 v[22:25], v2, s[18:19]
	global_load_dwordx4 v[14:17], v2, s[18:19] offset:1024
	global_load_dwordx4 v[6:9], v2, s[18:19] offset:2048
	s_nop 0
	global_load_dwordx4 v[2:5], v2, s[18:19] offset:3072
	s_nop 0
	global_load_dwordx4 v[30:33], v[10:11], off
	global_load_dwordx4 v[26:29], v[10:11], off offset:1024
	global_load_dwordx4 v[18:21], v[10:11], off offset:2048
	s_nop 0
	global_load_dwordx4 v[10:13], v[10:11], off offset:3072
	s_lshl_b64 s[20:21], s[20:21], 15
	s_add_u32 s20, s8, s20
	s_addc_u32 s21, s9, s21
	s_add_u32 s22, s4, s22
	s_addc_u32 s23, s5, s23
	s_lshl_b64 s[24:25], s[24:25], 15
	s_add_u32 s24, s8, s24
	s_addc_u32 s25, s9, s25
	s_ashr_i32 s29, s28, 31
	s_ashr_i32 s35, s34, 31
	s_lshl_b64 s[30:31], s[34:35], 17
	s_lshl_b64 s[26:27], s[28:29], 17
	s_add_u32 s26, s4, s26
	s_addc_u32 s27, s5, s27
	s_lshl_b64 s[28:29], s[28:29], 15
	s_add_u32 s28, s8, s28
	s_addc_u32 s29, s9, s29
	s_add_u32 s30, s4, s30
	s_addc_u32 s31, s5, s31
	s_lshl_b64 s[4:5], s[34:35], 15
	s_add_u32 s34, s8, s4
	s_movk_i32 s4, 0x60
	v_bitop3_b32 v36, v0, s4, v161 bitop3:0x6c
	s_movk_i32 s4, 0x80
	v_add_u32_e32 v44, s10, v36
	v_bitop3_b32 v36, v0, s4, v161 bitop3:0x6c
	s_movk_i32 s4, 0xa0
	v_add_u32_e32 v45, s10, v36
	v_bitop3_b32 v36, v0, s4, v161 bitop3:0x6c
	s_movk_i32 s4, 0xc0
	v_add_u32_e32 v47, s10, v36
	v_bitop3_b32 v36, v0, s4, v161 bitop3:0x6c
	s_movk_i32 s4, 0xe0
	v_add_u32_e32 v48, s10, v36
	v_bitop3_b32 v36, v0, s4, v161 bitop3:0x6c
	v_add_u32_e32 v49, s10, v36
	v_lshlrev_b32_e32 v36, 1, v155
	v_and_b32_e32 v50, 14, v36
	v_bitop3_b32 v36, v36, v35, 14 bitop3:0x6c
	v_lshlrev_b32_e32 v51, 4, v36
	v_bitop3_b32 v36, v35, v50, 4 bitop3:0x36
	v_lshlrev_b32_e32 v52, 4, v36
	v_bitop3_b32 v36, v35, v50, 8 bitop3:0x36
	v_lshlrev_b32_e32 v53, 4, v36
	v_bitop3_b32 v36, v35, v50, 12 bitop3:0x36
	v_lshlrev_b32_e32 v54, 4, v36
	v_bitop3_b32 v36, v35, v50, 16 bitop3:0x36
	v_lshlrev_b32_e32 v55, 4, v36
	v_bitop3_b32 v36, v35, v50, 20 bitop3:0x36
	v_lshlrev_b32_e32 v56, 4, v36
	v_bitop3_b32 v36, v35, v50, 24 bitop3:0x36
	v_lshlrev_b32_e32 v57, 4, v36
	v_bitop3_b32 v36, v35, v50, 28 bitop3:0x36
	v_lshlrev_b32_e32 v50, 4, v36
	v_lshl_or_b32 v35, v35, 2, v37
	v_bfe_u32 v36, v34, 1, 1
	v_lshlrev_b32_e32 v34, 3, v34
	v_and_b32_e32 v58, 8, v34
	v_lshlrev_b32_e32 v34, 1, v35
	v_and_b32_e32 v37, 14, v34
	v_or_b32_e32 v37, v37, v36
	v_lshl_add_u32 v35, v35, 9, s10
	v_lshl_add_u32 v59, v37, 4, v35
	v_or_b32_e32 v37, 2, v36
	v_bitop3_b32 v37, v34, v37, 14 bitop3:0x6c
	v_lshl_add_u32 v60, v37, 4, v35
	v_or_b32_e32 v37, 4, v36
	v_bitop3_b32 v37, v34, v37, 14 bitop3:0x6c
	v_lshl_add_u32 v61, v37, 4, v35
	v_or_b32_e32 v37, 6, v36
	v_bitop3_b32 v37, v34, v37, 14 bitop3:0x6c
	v_lshl_add_u32 v62, v37, 4, v35
	v_or_b32_e32 v37, 8, v36
	v_bitop3_b32 v37, v34, v37, 14 bitop3:0x6c
	v_lshl_add_u32 v63, v37, 4, v35
	v_or_b32_e32 v37, 10, v36
	v_bitop3_b32 v37, v34, v37, 14 bitop3:0x6c
	v_lshl_add_u32 v64, v37, 4, v35
	v_or_b32_e32 v37, 12, v36
	v_bitop3_b32 v37, v34, v37, 14 bitop3:0x6c
	v_lshl_add_u32 v65, v37, 4, v35
	v_bitop3_b32 v37, v34, v36, 14 bitop3:0x4e
	v_lshl_add_u32 v66, v37, 4, v35
	v_or_b32_e32 v37, v34, v36
	v_lshl_or_b32 v37, v37, 4, v162
	v_add_u32_e32 v67, v35, v37
	v_or_b32_e32 v37, 18, v36
	v_bitop3_b32 v37, v34, v37, 14 bitop3:0x6c
	v_lshl_add_u32 v68, v37, 4, v35
	v_or_b32_e32 v37, 20, v36
	v_bitop3_b32 v37, v34, v37, 14 bitop3:0x6c
	v_lshl_add_u32 v69, v37, 4, v35
	v_or_b32_e32 v37, 22, v36
	s_addc_u32 s35, s9, s5
	v_bitop3_b32 v37, v34, v37, 14 bitop3:0x6c
	v_lshl_add_u32 v70, v37, 4, v35
	v_or_b32_e32 v37, 24, v36
	s_add_u32 s1, s12, s1
	v_bitop3_b32 v37, v34, v37, 14 bitop3:0x6c
	s_addc_u32 s2, s13, s2
	v_lshl_add_u32 v71, v37, 4, v35
	v_or_b32_e32 v37, 26, v36
	s_mul_i32 s2, s2, 0x28000
	s_mul_hi_u32 s4, s1, 0x28000
	v_bitop3_b32 v37, v34, v37, 14 bitop3:0x6c
	s_add_i32 s2, s4, s2
	s_mul_i32 s1, s1, 0x28000
	v_lshl_add_u32 v72, v37, 4, v35
	v_or_b32_e32 v37, 28, v36
	v_or_b32_e32 v36, 30, v36
	s_add_u32 s4, s75, s1
	v_bitop3_b32 v37, v34, v37, 14 bitop3:0x6c
	v_bitop3_b32 v34, v34, v36, 14 bitop3:0x6c
	s_addc_u32 s5, s76, s2
	v_lshl_add_u32 v73, v37, 4, v35
	v_lshl_add_u32 v74, v34, 4, v35
	v_lshl_add_u64 v[152:153], s[4:5], 0, v[0:1]
	v_mov_b32_e32 v36, v1
	v_mov_b32_e32 v37, v1
	v_lshlrev_b32_e32 v0, 2, v38
	v_add_u32_e32 v38, 0, v39
	v_mov_b32_e32 v34, v1
	v_mov_b32_e32 v35, v1
	v_add_u32_e32 v166, v59, v58
	v_add_u32_e32 v167, v60, v58
	v_add_u32_e32 v168, v61, v58
	v_add_u32_e32 v169, v62, v58
	v_add_u32_e32 v170, v63, v58
	v_add_u32_e32 v171, v64, v58
	v_add_u32_e32 v172, v65, v58
	v_add_u32_e32 v173, v66, v58
	v_add_u32_e32 v174, v67, v58
	v_add_u32_e32 v175, v68, v58
	v_add_u32_e32 v176, v69, v58
	v_add_u32_e32 v177, v70, v58
	v_add_u32_e32 v178, v71, v58
	v_add_u32_e32 v179, v72, v58
	v_add_u32_e32 v180, v73, v58
	v_add_u32_e32 v181, v74, v58
	v_add_u32_e32 v185, v44, v40
	v_add_u32_e32 v186, v45, v40
	v_add_u32_e32 v187, v47, v40
	v_add_u32_e32 v188, v48, v40
	v_add_u32_e32 v189, v49, v40
	v_add_u32_e32 v190, v46, v51
	v_add_u32_e32 v191, 0x21000, v38
	v_add_u32_e32 v192, v46, v52
	v_add_u32_e32 v193, v46, v53
	v_add_u32_e32 v194, v46, v54
	v_add_u32_e32 v195, v46, v55
	v_add_u32_e32 v196, v46, v56
	v_add_u32_e32 v197, v46, v57
	v_add_u32_e32 v198, v46, v50
	v_mov_b64_e32 v[96:97], v[36:37]
	v_mov_b64_e32 v[92:93], v[36:37]
	v_mov_b64_e32 v[88:89], v[36:37]
	v_mov_b64_e32 v[84:85], v[36:37]
	v_mov_b64_e32 v[80:81], v[36:37]
	v_mov_b64_e32 v[76:77], v[36:37]
	v_mov_b64_e32 v[72:73], v[36:37]
	v_mov_b64_e32 v[68:69], v[36:37]
	v_mov_b64_e32 v[64:65], v[36:37]
	v_mov_b64_e32 v[60:61], v[36:37]
	v_mov_b64_e32 v[56:57], v[36:37]
	v_mov_b64_e32 v[52:53], v[36:37]
	v_mov_b64_e32 v[48:49], v[36:37]
	v_mov_b64_e32 v[44:45], v[36:37]
	v_mov_b64_e32 v[40:41], v[36:37]
	v_mov_b64_e32 v[94:95], v[34:35]
	v_mov_b64_e32 v[90:91], v[34:35]
	v_mov_b64_e32 v[86:87], v[34:35]
	v_mov_b64_e32 v[82:83], v[34:35]
	v_mov_b64_e32 v[78:79], v[34:35]
	v_mov_b64_e32 v[74:75], v[34:35]
	v_mov_b64_e32 v[70:71], v[34:35]
	v_mov_b64_e32 v[66:67], v[34:35]
	v_mov_b64_e32 v[62:63], v[34:35]
	v_mov_b64_e32 v[58:59], v[34:35]
	v_mov_b64_e32 v[54:55], v[34:35]
	v_mov_b64_e32 v[50:51], v[34:35]
	v_mov_b64_e32 v[46:47], v[34:35]
	v_mov_b64_e32 v[42:43], v[34:35]
	v_mov_b64_e32 v[38:39], v[34:35]
	s_branch .LBB0_2270

.LBB0_2494:
	s_load_dwordx2 s[4:5], s[4:5], 0x10
	s_nop 0
	s_load_dwordx2 s[8:9], s[8:9], 0x18
	s_nop 0
	s_load_dwordx2 s[12:13], s[12:13], 0x20
	v_and_b32_e32 v155, 15, v34
	s_andn2_b64 vcc, exec, s[14:15]
	s_lshl_b32 s98, s1, 2
	s_add_i32 s98, s55, s98
	s_ashr_i32 s99, s98, 31
	s_lshl_b64 s[98:99], s[98:99], 2
	s_waitcnt lgkmcnt(0)
	s_add_u32 s98, s12, s98
	s_addc_u32 s99, s13, s99
	global_load_dwordx4 v[236:239], v1, s[98:99]
	s_cbranch_vccnz .LBB0_2498
	s_lshl_b32 s14, s1, 10
	s_add_i32 s14, s14, 0
	s_add_i32 s14, s14, 0x21000
	v_add_u32_e32 v3, s14, v2
	s_lshl_b32 s14, s1, 5
	s_ashr_i32 s15, s14, 31
	v_mul_u32_u24_e32 v6, 0x140, v155
	s_lshl_b64 s[14:15], s[14:15], 1
	v_mov_b64_e32 v[150:151], v[0:1]
	v_and_or_b32 v4, v34, 48, s14
	v_mov_b32_e32 v5, s15
	v_lshlrev_b32_e32 v0, 1, v6
	v_lshl_add_u64 v[4:5], v[4:5], 0, v[0:1]
	s_add_i32 s2, s1, -8
	v_lshl_add_u64 v[4:5], s[88:89], 0, v[4:5]
.LBB0_2496:
	global_load_dwordx4 v[6:9], v[4:5], off
	s_add_i32 s2, s2, 8
	s_mov_b64 s[14:15], 0x200
	v_lshl_add_u64 v[4:5], v[4:5], 0, s[14:15]
	s_cmp_gt_i32 s2, 1
	s_cbranch_scc1 .Lmy_q1_a2b
	global_load_dwordx4 v[248:251], v[4:5], off
	s_add_i32 s2, s2, 8
	v_lshl_add_u64 v[4:5], v[4:5], 0, s[14:15]
	s_waitcnt vmcnt(0)
	ds_write_b128 v3, v[6:9]
	v_add_u32_e32 v3, 0x2000, v3
	ds_write_b128 v3, v[248:251]
	v_add_u32_e32 v3, 0x2000, v3
	s_cmp_gt_i32 s2, 1
	s_cbranch_scc0 .LBB0_2496
	s_branch .Lmy_q2_a2b

.LBB0_2498:
	s_lshl_b32 s14, s1, 2
	s_add_i32 s14, s55, s14
	s_lshl_b32 s2, s1, 14
	s_ashr_i32 s15, s14, 31
	s_add_i32 s2, s2, 0
	s_lshl_b64 s[14:15], s[14:15], 2
	s_waitcnt lgkmcnt(0)
	s_add_u32 s12, s12, s14
	s_addc_u32 s13, s13, s15
	v_mov_b32_e32 v3, v1
	s_barrier
	v_lshlrev_b32_e32 v0, 3, v36
	v_lshlrev_b32_e32 v38, 2, v36
	v_and_b32_e32 v36, 0x1f0, v0
	v_add_u32_e32 v41, s2, v36
	v_xad_u32 v42, v36, 32, s2
	v_xad_u32 v43, v36, 64, s2
	v_lshrrev_b32_e32 v37, 2, v155
	v_lshl_add_u32 v46, v155, 9, s2
	v_and_b32_e32 v40, 8, v0
	v_xor_b32_e32 v165, 64, v38
	v_xor_b32_e32 v164, 0x80, v38
	v_add_u32_e32 v183, v41, v40
	v_add_u32_e32 v184, v42, v40
	v_add_u32_e32 v185, v43, v40
	s_mov_b32 s30, 4
	s_mov_b32 s31, 0
	v_mov_b32_e32 v166, 0
	v_mov_b32_e32 v154, 0xf149f2ca
	s_movk_i32 s34, 0x2000
	s_waitcnt vmcnt(0)
	v_readfirstlane_b32 s18, v237
	v_readfirstlane_b32 s14, v236
	s_ashr_i32 s15, s14, 31
	s_ashr_i32 s19, s18, 31
	s_lshl_b64 s[16:17], s[18:19], 17
	s_lshl_b64 s[12:13], s[14:15], 17
	s_add_u32 s12, s4, s12
	s_addc_u32 s13, s5, s13
	v_lshl_add_u64 v[10:11], s[12:13], 0, v[2:3]
	v_add_co_u32_e32 v10, vcc, s63, v10
	v_readfirstlane_b32 s26, v239
	s_nop 0
	v_addc_co_u32_e32 v11, vcc, 0, v11, vcc
	v_readfirstlane_b32 s22, v238
	global_load_dwordx4 v[22:25], v2, s[12:13]
	global_load_dwordx4 v[14:17], v2, s[12:13] offset:1024
	global_load_dwordx4 v[6:9], v2, s[12:13] offset:2048
	s_nop 0
	global_load_dwordx4 v[2:5], v2, s[12:13] offset:3072
	s_nop 0
	global_load_dwordx4 v[30:33], v[10:11], off
	global_load_dwordx4 v[26:29], v[10:11], off offset:1024
	global_load_dwordx4 v[18:21], v[10:11], off offset:2048
	s_nop 0
	global_load_dwordx4 v[10:13], v[10:11], off offset:3072
	s_lshl_b64 s[14:15], s[14:15], 15
	s_add_u32 s14, s8, s14
	s_addc_u32 s15, s9, s15
	s_add_u32 s16, s4, s16
	s_addc_u32 s17, s5, s17
	s_lshl_b64 s[18:19], s[18:19], 15
	s_add_u32 s18, s8, s18
	s_addc_u32 s19, s9, s19
	s_ashr_i32 s23, s22, 31
	s_ashr_i32 s27, s26, 31
	s_lshl_b64 s[24:25], s[26:27], 17
	s_lshl_b64 s[20:21], s[22:23], 17
	s_add_u32 s20, s4, s20
	s_addc_u32 s21, s5, s21
	s_lshl_b64 s[22:23], s[22:23], 15
	s_add_u32 s22, s8, s22
	s_addc_u32 s23, s9, s23
	s_add_u32 s24, s4, s24
	s_addc_u32 s25, s5, s25
	s_lshl_b64 s[4:5], s[26:27], 15
	s_add_u32 s26, s8, s4
	s_movk_i32 s4, 0x60
	v_bitop3_b32 v36, v0, s4, v162 bitop3:0x6c
	s_movk_i32 s4, 0x80
	v_add_u32_e32 v44, s2, v36
	v_bitop3_b32 v36, v0, s4, v162 bitop3:0x6c
	s_movk_i32 s4, 0xa0
	v_add_u32_e32 v45, s2, v36
	v_bitop3_b32 v36, v0, s4, v162 bitop3:0x6c
	s_movk_i32 s4, 0xc0
	v_add_u32_e32 v47, s2, v36
	v_bitop3_b32 v36, v0, s4, v162 bitop3:0x6c
	s_movk_i32 s4, 0xe0
	v_add_u32_e32 v48, s2, v36
	v_bitop3_b32 v36, v0, s4, v162 bitop3:0x6c
	v_add_u32_e32 v49, s2, v36
	v_lshlrev_b32_e32 v36, 1, v155
	v_and_b32_e32 v57, 14, v36
	v_bitop3_b32 v36, v36, v35, 14 bitop3:0x6c
	v_lshlrev_b32_e32 v51, 4, v36
	v_bitop3_b32 v36, v35, v57, 4 bitop3:0x36
	v_lshlrev_b32_e32 v50, 4, v36
	v_bitop3_b32 v36, v35, v57, 8 bitop3:0x36
	v_lshlrev_b32_e32 v52, 4, v36
	v_bitop3_b32 v36, v35, v57, 12 bitop3:0x36
	v_lshlrev_b32_e32 v53, 4, v36
	v_bitop3_b32 v36, v35, v57, 16 bitop3:0x36
	v_lshlrev_b32_e32 v54, 4, v36
	v_bitop3_b32 v36, v35, v57, 20 bitop3:0x36
	v_lshlrev_b32_e32 v55, 4, v36
	v_bitop3_b32 v36, v35, v57, 24 bitop3:0x36
	v_lshlrev_b32_e32 v56, 4, v36
	v_bitop3_b32 v36, v35, v57, 28 bitop3:0x36
	v_lshlrev_b32_e32 v57, 4, v36
	v_lshl_or_b32 v35, v35, 2, v37
	v_bfe_u32 v36, v34, 1, 1
	v_lshlrev_b32_e32 v34, 3, v34
	v_and_b32_e32 v58, 8, v34
	v_lshlrev_b32_e32 v34, 1, v35
	v_and_b32_e32 v37, 14, v34
	v_or_b32_e32 v37, v37, v36
	v_lshl_add_u32 v35, v35, 9, s2
	v_lshl_add_u32 v59, v37, 4, v35
	v_or_b32_e32 v37, 2, v36
	v_bitop3_b32 v37, v34, v37, 14 bitop3:0x6c
	v_lshl_add_u32 v60, v37, 4, v35
	v_or_b32_e32 v37, 4, v36
	v_bitop3_b32 v37, v34, v37, 14 bitop3:0x6c
	v_lshl_add_u32 v61, v37, 4, v35
	v_or_b32_e32 v37, 6, v36
	v_bitop3_b32 v37, v34, v37, 14 bitop3:0x6c
	v_lshl_add_u32 v62, v37, 4, v35
	v_or_b32_e32 v37, 8, v36
	v_bitop3_b32 v37, v34, v37, 14 bitop3:0x6c
	v_lshl_add_u32 v63, v37, 4, v35
	v_or_b32_e32 v37, 10, v36
	v_bitop3_b32 v37, v34, v37, 14 bitop3:0x6c
	v_lshl_add_u32 v64, v37, 4, v35
	v_or_b32_e32 v37, 12, v36
	v_bitop3_b32 v37, v34, v37, 14 bitop3:0x6c
	v_lshl_add_u32 v65, v37, 4, v35
	v_bitop3_b32 v37, v34, v36, 14 bitop3:0x4e
	v_lshl_add_u32 v66, v37, 4, v35
	v_or_b32_e32 v37, v34, v36
	v_lshl_or_b32 v37, v37, 4, v163
	v_add_u32_e32 v67, v35, v37
	v_or_b32_e32 v37, 18, v36
	v_bitop3_b32 v37, v34, v37, 14 bitop3:0x6c
	v_lshl_add_u32 v68, v37, 4, v35
	v_or_b32_e32 v37, 20, v36
	v_bitop3_b32 v37, v34, v37, 14 bitop3:0x6c
	v_lshl_add_u32 v69, v37, 4, v35
	v_or_b32_e32 v37, 22, v36
	v_bitop3_b32 v37, v34, v37, 14 bitop3:0x6c
	v_lshl_add_u32 v70, v37, 4, v35
	v_or_b32_e32 v37, 24, v36
	v_bitop3_b32 v37, v34, v37, 14 bitop3:0x6c
	v_lshl_add_u32 v71, v37, 4, v35
	v_or_b32_e32 v37, 26, v36
	s_addc_u32 s27, s9, s5
	v_bitop3_b32 v37, v34, v37, 14 bitop3:0x6c
	s_mul_hi_i32 s2, s1, 0x28000
	s_mul_i32 s1, s1, 0x28000
	v_lshl_add_u32 v72, v37, 4, v35
	v_or_b32_e32 v37, 28, v36
	v_or_b32_e32 v36, 30, v36
	s_add_u32 s4, s64, s1
	v_bitop3_b32 v37, v34, v37, 14 bitop3:0x6c
	v_bitop3_b32 v34, v34, v36, 14 bitop3:0x6c
	s_addc_u32 s5, s65, s2
	v_lshl_add_u32 v73, v37, 4, v35
	v_lshl_add_u32 v74, v34, 4, v35
	v_lshl_add_u64 v[152:153], s[4:5], 0, v[0:1]
	v_mov_b32_e32 v36, v1
	v_mov_b32_e32 v37, v1
	v_lshlrev_b32_e32 v0, 2, v38
	v_add_u32_e32 v38, 0, v39
	v_mov_b32_e32 v34, v1
	v_mov_b32_e32 v35, v1
	v_add_u32_e32 v167, v59, v58
	v_add_u32_e32 v168, v60, v58
	v_add_u32_e32 v169, v61, v58
	v_add_u32_e32 v170, v62, v58
	v_add_u32_e32 v171, v63, v58
	v_add_u32_e32 v172, v64, v58
	v_add_u32_e32 v173, v65, v58
	v_add_u32_e32 v174, v66, v58
	v_add_u32_e32 v175, v67, v58
	v_add_u32_e32 v176, v68, v58
	v_add_u32_e32 v177, v69, v58
	v_add_u32_e32 v178, v70, v58
	v_add_u32_e32 v179, v71, v58
	v_add_u32_e32 v180, v72, v58
	v_add_u32_e32 v181, v73, v58
	v_add_u32_e32 v182, v74, v58
	v_add_u32_e32 v186, v44, v40
	v_add_u32_e32 v187, v45, v40
	v_add_u32_e32 v188, v47, v40
	v_add_u32_e32 v189, v48, v40
	v_add_u32_e32 v190, v49, v40
	v_add_u32_e32 v191, v46, v51
	v_add_u32_e32 v192, 0x21000, v38
	v_add_u32_e32 v193, v46, v50
	v_add_u32_e32 v194, v46, v52
	v_add_u32_e32 v195, v46, v53
	v_add_u32_e32 v196, v46, v54
	v_add_u32_e32 v197, v46, v55
	v_add_u32_e32 v198, v46, v56
	v_add_u32_e32 v199, v46, v57
	v_mov_b64_e32 v[96:97], v[36:37]
	v_mov_b64_e32 v[92:93], v[36:37]
	v_mov_b64_e32 v[88:89], v[36:37]
	v_mov_b64_e32 v[84:85], v[36:37]
	v_mov_b64_e32 v[80:81], v[36:37]
	v_mov_b64_e32 v[76:77], v[36:37]
	v_mov_b64_e32 v[72:73], v[36:37]
	v_mov_b64_e32 v[68:69], v[36:37]
	v_mov_b64_e32 v[64:65], v[36:37]
	v_mov_b64_e32 v[60:61], v[36:37]
	v_mov_b64_e32 v[56:57], v[36:37]
	v_mov_b64_e32 v[52:53], v[36:37]
	v_mov_b64_e32 v[48:49], v[36:37]
	v_mov_b64_e32 v[44:45], v[36:37]
	v_mov_b64_e32 v[40:41], v[36:37]
	v_mov_b64_e32 v[94:95], v[34:35]
	v_mov_b64_e32 v[90:91], v[34:35]
	v_mov_b64_e32 v[86:87], v[34:35]
	v_mov_b64_e32 v[82:83], v[34:35]
	v_mov_b64_e32 v[78:79], v[34:35]
	v_mov_b64_e32 v[74:75], v[34:35]
	v_mov_b64_e32 v[70:71], v[34:35]
	v_mov_b64_e32 v[66:67], v[34:35]
	v_mov_b64_e32 v[62:63], v[34:35]
	v_mov_b64_e32 v[58:59], v[34:35]
	v_mov_b64_e32 v[54:55], v[34:35]
	v_mov_b64_e32 v[50:51], v[34:35]
	v_mov_b64_e32 v[46:47], v[34:35]
	v_mov_b64_e32 v[42:43], v[34:35]
	v_mov_b64_e32 v[38:39], v[34:35]
	s_branch .LBB0_2500

.LBB0_3628:
	global_load_dwordx4 v[10:13], v[2:3], off
	s_add_i32 s1, s1, 8
	s_mov_b64 s[8:9], 0x200
	v_lshl_add_u64 v[2:3], v[2:3], 0, s[8:9]
	s_cmp_gt_i32 s1, 1
	s_cbranch_scc1 .Lmy_q1_a3a
	global_load_dwordx4 v[248:251], v[2:3], off
	s_add_i32 s1, s1, 8
	v_lshl_add_u64 v[2:3], v[2:3], 0, s[8:9]
	s_waitcnt vmcnt(0)
	ds_write_b128 v4, v[10:13]
	v_add_u32_e32 v4, 0x2000, v4
	ds_write_b128 v4, v[248:251]
	v_add_u32_e32 v4, 0x2000, v4
	s_cmp_gt_i32 s1, 1
	s_cbranch_scc0 .LBB0_3628
	s_branch .Lmy_q2_a3a
.Lmy_q1_a3a:
	s_waitcnt vmcnt(0)
	ds_write_b128 v4, v[10:13]
	v_add_u32_e32 v4, 0x2000, v4
.Lmy_q2_a3a:
	v_mov_b32_e32 v4, v8

.LBB0_3807:
	global_load_dwordx4 v[10:13], v[2:3], off
	s_add_i32 s1, s1, 8
	s_mov_b64 s[4:5], 0x200
	v_lshl_add_u64 v[2:3], v[2:3], 0, s[4:5]
	s_cmp_gt_i32 s1, 1
	s_cbranch_scc1 .Lmy_q1_a3b
	global_load_dwordx4 v[248:251], v[2:3], off
	s_add_i32 s1, s1, 8
	v_lshl_add_u64 v[2:3], v[2:3], 0, s[4:5]
	s_waitcnt vmcnt(0)
	ds_write_b128 v4, v[10:13]
	v_add_u32_e32 v4, 0x2000, v4
	ds_write_b128 v4, v[248:251]
	v_add_u32_e32 v4, 0x2000, v4
	s_cmp_gt_i32 s1, 1
	s_cbranch_scc0 .LBB0_3807
	s_branch .Lmy_q2_a3b
